# v36 + nt on the FFN-down A-operand (512 MiB hidden activations) LDS-DMA loads so they do not evict the weight panel from MALL
# baseline (speedup 1.0000x reference)
;     __device__ __forceinline__ size_t a_koff(int t) const { return (size_t)t * 128; }
;     __device__ __forceinline__ size_t a_koff(int t) const { return (size_t)t * 32768; }
; #define PG8_STAGE(bufoff, gbase, voff) do { _Pragma("unroll") for (int _i = 0; _i < 2; ++_i) \
;         __builtin_amdgcn_global_load_lds((const unsigned*)((const char*)(gbase) + (size_t)_i * p##voff + (voff)), (LAS unsigned*)(lds + (bufoff) + ldsw + _i * 8192), 16, 0, 0); } while (0)
; #define PG8_LDA(dst, b, h) do { _Pragma("unroll") for (int m = 0; m < 4; ++m) _Pragma("unroll") for (int k = 0; k < 2; ++k) dst[m][k] = *(const LAS bf16x8*)(lds + PG8_SA(b, h) + aoff + m * 2048 + k * 1024); } while (0)
; #define PG8_LDB(dst, b, h) do { _Pragma("unroll") for (int n = 0; n < 2; ++n) _Pragma("unroll") for (int k = 0; k < 2; ++k) dst[n][k] = *(const LAS bf16x8*)(lds + PG8_SB(b, h) + boff + n * 2048 + k * 1024); } while (0)
; #define PG8_WAIT_V(n) asm volatile("s_waitcnt vmcnt(" #n ")" ::: "memory")
; #define PG8_WAIT_L(n) asm volatile("s_waitcnt lgkmcnt(" #n ")" ::: "memory")
; #define PG8_BAR __builtin_amdgcn_s_barrier()
; #define PG8_SCHED __builtin_amdgcn_sched_barrier(0)
;     __device__ __forceinline__ size_t a_koff(int t) const { return ((size_t)(t >> 1) * 3072 + (size_t)(t & 1) * 64) * 2; }
;     __device__ __forceinline__ size_t a_koff(int t) const { return (size_t)t * 128; }
;     ...
;             const char* a1 = cA + g.a_koff(t + 1);
;             const char* a2 = last ? nA : cA + g.a_koff(t + 2); const char* b2 = last ? nB : cB + (size_t)(t + 2) * kstep;
;             const char* a3 = last ? nA + g.a_koff(1) : cA + g.a_koff(t + 3); const char* b3 = b2 + kstep;
;             PG8_LDB(B0, 0, 0); PG8_LDB(B1, 0, 1); PG8_SCHED; PG8_LDA(At, 0, 0); PG8_STAGE(PG8_SA(1, 1), a1 + hstepA, voffA);
;             PG8_WAIT_V(8); PG8_WAIT_L(0); PG8_BAR; PG8_MMA(0, 0, At, B0); PG8_MMA(0, 1, At, B1); PG8_BAR; PG8_SCHED;
;             PG8_LDA(At, 0, 1); PG8_STAGE(PG8_SB(0, 0), b2, voffB); PG8_STAGE(PG8_SB(0, 1), b2 + hstepB, voffB); PG8_STAGE(PG8_SA(0, 0), a2, voffA);
;             PG8_WAIT_V(8); PG8_WAIT_L(0); PG8_BAR; PG8_MMA(1, 0, At, B0); PG8_MMA(1, 1, At, B1); PG8_BAR; PG8_SCHED;
.LBB0_1281:
	ds_read_b128 v[142:145], v188
	ds_read_b128 v[146:149], v188 offset:1024
	ds_read_b128 v[150:153], v188 offset:2048
	ds_read_b128 v[154:157], v188 offset:3072
	ds_read_b128 v[158:161], v189
	ds_read_b128 v[162:165], v189 offset:1024
	ds_read_b128 v[166:169], v189 offset:2048
	ds_read_b128 v[170:173], v189 offset:3072
	s_add_u32 s50, s44, s48
	s_addc_u32 s51, s45, s49
	s_add_u32 s83, s50, 0x10000
	s_addc_u32 s86, s51, 0
	s_add_u32 s50, s50, 0x18000
	s_addc_u32 s51, s51, 0
	s_cmp_eq_u32 s48, 0x7f0000
	s_cselect_b32 s51, s79, s51
	s_cselect_b32 s50, s78, s50
	s_cselect_b32 s85, s35, s81
	s_cselect_b32 s84, s47, s80
	s_cselect_b32 s87, s37, s86
	s_cselect_b32 s86, s43, s83
	v_lshl_add_u64 v[212:213], v[140:141], 0, s[48:49]
	s_mov_b64 s[88:89], 0xc000
	v_lshl_add_u64 v[214:215], v[212:213], 0, s[88:89]
	s_add_i32 m0, s57, 0xc000
	s_mov_b64 s[88:89], 0xe000
	ds_read_b128 v[174:177], v190
	ds_read_b128 v[178:181], v190 offset:1024
	ds_read_b128 v[182:185], v190 offset:2048
	ds_read_b128 v[192:195], v190 offset:3072
	ds_read_b128 v[196:199], v190 offset:4096
	ds_read_b128 v[200:203], v190 offset:5120
	ds_read_b128 v[204:207], v190 offset:6144
	ds_read_b128 v[208:211], v190 offset:7168
	global_load_lds_dwordx4 v[214:215], off nt
	v_lshl_add_u64 v[212:213], v[212:213], 0, s[88:89]
	s_add_i32 m0, s57, 0xe000
	s_nop 0
	global_load_lds_dwordx4 v[212:213], off nt
	s_waitcnt vmcnt(8)
	s_waitcnt lgkmcnt(0)
	s_barrier
	s_setprio 1
	s_waitcnt lgkmcnt(0)
	v_mfma_f32_16x16x32_bf16 v[124:127], v[142:145], v[174:177], v[124:127]
	v_mfma_f32_16x16x32_bf16 v[124:127], v[146:149], v[178:181], v[124:127]
	v_mfma_f32_16x16x32_bf16 v[120:123], v[150:153], v[174:177], v[120:123]
	v_mfma_f32_16x16x32_bf16 v[120:123], v[154:157], v[178:181], v[120:123]
	v_mfma_f32_16x16x32_bf16 v[116:119], v[142:145], v[182:185], v[116:119]
	v_mfma_f32_16x16x32_bf16 v[116:119], v[146:149], v[192:195], v[116:119]
	v_mfma_f32_16x16x32_bf16 v[112:115], v[150:153], v[182:185], v[112:115]
	v_mfma_f32_16x16x32_bf16 v[112:115], v[154:157], v[192:195], v[112:115]
	v_mfma_f32_16x16x32_bf16 v[108:111], v[142:145], v[196:199], v[108:111]
	v_mfma_f32_16x16x32_bf16 v[108:111], v[146:149], v[200:203], v[108:111]
	v_mfma_f32_16x16x32_bf16 v[104:107], v[150:153], v[196:199], v[104:107]
	v_mfma_f32_16x16x32_bf16 v[104:107], v[154:157], v[200:203], v[104:107]
	v_mfma_f32_16x16x32_bf16 v[100:103], v[142:145], v[204:207], v[100:103]
	v_mfma_f32_16x16x32_bf16 v[100:103], v[146:149], v[208:211], v[100:103]
	v_mfma_f32_16x16x32_bf16 v[96:99], v[150:153], v[204:207], v[96:99]
	v_mfma_f32_16x16x32_bf16 v[96:99], v[154:157], v[208:211], v[96:99]
	s_setprio 0
	s_setprio 1
	v_mfma_f32_16x16x32_bf16 v[60:63], v[158:161], v[174:177], v[60:63]
	v_mfma_f32_16x16x32_bf16 v[60:63], v[162:165], v[178:181], v[60:63]
	v_mfma_f32_16x16x32_bf16 v[56:59], v[166:169], v[174:177], v[56:59]
	v_mfma_f32_16x16x32_bf16 v[56:59], v[170:173], v[178:181], v[56:59]
	v_mfma_f32_16x16x32_bf16 v[52:55], v[158:161], v[182:185], v[52:55]
	v_mfma_f32_16x16x32_bf16 v[52:55], v[162:165], v[192:195], v[52:55]
	v_mfma_f32_16x16x32_bf16 v[48:51], v[166:169], v[182:185], v[48:51]
	v_mfma_f32_16x16x32_bf16 v[48:51], v[170:173], v[192:195], v[48:51]
	v_mfma_f32_16x16x32_bf16 v[44:47], v[158:161], v[196:199], v[44:47]
	v_mfma_f32_16x16x32_bf16 v[44:47], v[162:165], v[200:203], v[44:47]
	v_mfma_f32_16x16x32_bf16 v[40:43], v[166:169], v[196:199], v[40:43]
	v_mfma_f32_16x16x32_bf16 v[40:43], v[170:173], v[200:203], v[40:43]
	v_mfma_f32_16x16x32_bf16 v[36:39], v[158:161], v[204:207], v[36:39]
	v_mfma_f32_16x16x32_bf16 v[36:39], v[162:165], v[208:211], v[36:39]
	v_mfma_f32_16x16x32_bf16 v[32:35], v[166:169], v[204:207], v[32:35]
	v_mfma_f32_16x16x32_bf16 v[32:35], v[170:173], v[208:211], v[32:35]
	s_setprio 0
	s_barrier
	s_add_i32 s83, s94, s56
	v_lshl_add_u64 v[212:213], s[84:85], 0, v[130:131]
	s_mov_b32 m0, s83
	ds_read_b128 v[174:177], v190 offset:16384
	ds_read_b128 v[178:181], v190 offset:17408
	ds_read_b128 v[182:185], v190 offset:18432
	ds_read_b128 v[192:195], v190 offset:19456
	ds_read_b128 v[196:199], v190 offset:20480
	ds_read_b128 v[200:203], v190 offset:21504
	ds_read_b128 v[204:207], v190 offset:22528
	ds_read_b128 v[208:211], v190 offset:23552
	global_load_lds_dwordx4 v[212:213], off
	v_lshl_add_u64 v[214:215], v[212:213], 0, s[4:5]
	s_add_i32 m0, s83, 0x2000
	s_add_i32 s83, s95, s56
	global_load_lds_dwordx4 v[214:215], off
	v_lshl_add_u64 v[214:215], v[212:213], 0, s[6:7]
	s_mov_b32 m0, s83
	s_nop 0
	global_load_lds_dwordx4 v[214:215], off
	v_lshl_add_u64 v[214:215], v[212:213], 0, s[8:9]
	s_add_i32 m0, s83, 0x2000
	s_nop 0
	global_load_lds_dwordx4 v[214:215], off
	v_lshl_add_u64 v[214:215], s[86:87], 0, v[128:129]
	s_mov_b32 m0, s57
	v_lshl_add_u64 v[216:217], v[214:215], 0, s[10:11]
	global_load_lds_dwordx4 v[214:215], off nt
	s_mov_b32 m0, s58
	s_nop 0
	global_load_lds_dwordx4 v[216:217], off nt
	s_waitcnt vmcnt(8)
	s_waitcnt lgkmcnt(0)
	s_barrier
; #define PG8_STAGE(bufoff, gbase, voff) do { _Pragma("unroll") for (int _i = 0; _i < 2; ++_i) \
;         __builtin_amdgcn_global_load_lds((const unsigned*)((const char*)(gbase) + (size_t)_i * p##voff + (voff)), (LAS unsigned*)(lds + (bufoff) + ldsw + _i * 8192), 16, 0, 0); } while (0)
; #define PG8_LDA(dst, b, h) do { _Pragma("unroll") for (int m = 0; m < 4; ++m) _Pragma("unroll") for (int k = 0; k < 2; ++k) dst[m][k] = *(const LAS bf16x8*)(lds + PG8_SA(b, h) + aoff + m * 2048 + k * 1024); } while (0)
; #define PG8_LDB(dst, b, h) do { _Pragma("unroll") for (int n = 0; n < 2; ++n) _Pragma("unroll") for (int k = 0; k < 2; ++k) dst[n][k] = *(const LAS bf16x8*)(lds + PG8_SB(b, h) + boff + n * 2048 + k * 1024); } while (0)
; #define PG8_WAIT_V(n) asm volatile("s_waitcnt vmcnt(" #n ")" ::: "memory")
; #define PG8_WAIT_L(n) asm volatile("s_waitcnt lgkmcnt(" #n ")" ::: "memory")
; #define PG8_BAR __builtin_amdgcn_s_barrier()
; #define PG8_SCHED __builtin_amdgcn_sched_barrier(0)
;     ...
;             PG8_WAIT_V(8); PG8_WAIT_L(0); PG8_BAR; PG8_MMA(1, 0, At, B0); PG8_MMA(1, 1, At, B1); PG8_BAR; PG8_SCHED;
;             PG8_LDB(B0, 1, 0); PG8_LDB(B1, 1, 1); PG8_SCHED; PG8_LDA(At, 1, 0); PG8_STAGE(PG8_SA(0, 1), a2 + hstepA, voffA);
;             PG8_WAIT_V(8); PG8_WAIT_L(0); PG8_BAR; PG8_MMA(0, 0, At, B0); PG8_MMA(0, 1, At, B1); PG8_BAR; PG8_SCHED;
;             PG8_LDA(At, 1, 1); PG8_STAGE(PG8_SB(1, 0), b3, voffB); PG8_STAGE(PG8_SB(1, 1), b3 + hstepB, voffB); PG8_STAGE(PG8_SA(1, 0), a3, voffA);
	s_setprio 1
	s_waitcnt lgkmcnt(0)
	v_mfma_f32_16x16x32_bf16 v[92:95], v[142:145], v[174:177], v[92:95]
	v_mfma_f32_16x16x32_bf16 v[92:95], v[146:149], v[178:181], v[92:95]
	v_mfma_f32_16x16x32_bf16 v[88:91], v[150:153], v[174:177], v[88:91]
	v_mfma_f32_16x16x32_bf16 v[88:91], v[154:157], v[178:181], v[88:91]
	v_mfma_f32_16x16x32_bf16 v[84:87], v[142:145], v[182:185], v[84:87]
	v_mfma_f32_16x16x32_bf16 v[84:87], v[146:149], v[192:195], v[84:87]
	v_mfma_f32_16x16x32_bf16 v[80:83], v[150:153], v[182:185], v[80:83]
	v_mfma_f32_16x16x32_bf16 v[80:83], v[154:157], v[192:195], v[80:83]
	v_mfma_f32_16x16x32_bf16 v[76:79], v[142:145], v[196:199], v[76:79]
	v_mfma_f32_16x16x32_bf16 v[76:79], v[146:149], v[200:203], v[76:79]
	v_mfma_f32_16x16x32_bf16 v[72:75], v[150:153], v[196:199], v[72:75]
	v_mfma_f32_16x16x32_bf16 v[72:75], v[154:157], v[200:203], v[72:75]
	v_mfma_f32_16x16x32_bf16 v[68:71], v[142:145], v[204:207], v[68:71]
	v_mfma_f32_16x16x32_bf16 v[68:71], v[146:149], v[208:211], v[68:71]
	v_mfma_f32_16x16x32_bf16 v[64:67], v[150:153], v[204:207], v[64:67]
	v_mfma_f32_16x16x32_bf16 v[64:67], v[154:157], v[208:211], v[64:67]
	s_setprio 0
	s_setprio 1
	v_mfma_f32_16x16x32_bf16 v[28:31], v[158:161], v[174:177], v[28:31]
	v_mfma_f32_16x16x32_bf16 v[28:31], v[162:165], v[178:181], v[28:31]
	v_mfma_f32_16x16x32_bf16 v[24:27], v[166:169], v[174:177], v[24:27]
	v_mfma_f32_16x16x32_bf16 v[24:27], v[170:173], v[178:181], v[24:27]
	v_mfma_f32_16x16x32_bf16 v[20:23], v[158:161], v[182:185], v[20:23]
	v_mfma_f32_16x16x32_bf16 v[20:23], v[162:165], v[192:195], v[20:23]
	v_mfma_f32_16x16x32_bf16 v[16:19], v[166:169], v[182:185], v[16:19]
	v_mfma_f32_16x16x32_bf16 v[16:19], v[170:173], v[192:195], v[16:19]
	v_mfma_f32_16x16x32_bf16 v[12:15], v[158:161], v[196:199], v[12:15]
	v_mfma_f32_16x16x32_bf16 v[12:15], v[162:165], v[200:203], v[12:15]
	v_mfma_f32_16x16x32_bf16 v[8:11], v[166:169], v[196:199], v[8:11]
	v_mfma_f32_16x16x32_bf16 v[8:11], v[170:173], v[200:203], v[8:11]
	v_mfma_f32_16x16x32_bf16 v[4:7], v[158:161], v[204:207], v[4:7]
	v_mfma_f32_16x16x32_bf16 v[4:7], v[162:165], v[208:211], v[4:7]
	v_mfma_f32_16x16x32_bf16 v[0:3], v[166:169], v[204:207], v[0:3]
	v_mfma_f32_16x16x32_bf16 v[0:3], v[170:173], v[208:211], v[0:3]
	s_setprio 0
	s_barrier
	s_add_i32 s83, 0, 0x18000
	v_add_u32_e32 v132, s83, v187
	s_add_i32 s84, 0, 0x1c000
	ds_read_b128 v[142:145], v132
	ds_read_b128 v[146:149], v132 offset:1024
	ds_read_b128 v[150:153], v132 offset:2048
	ds_read_b128 v[154:157], v132 offset:3072
	v_add_u32_e32 v132, s84, v187
	ds_read_b128 v[158:161], v132
	ds_read_b128 v[162:165], v132 offset:1024
	ds_read_b128 v[166:169], v132 offset:2048
	ds_read_b128 v[170:173], v132 offset:3072
	s_mov_b32 m0, s59
	v_lshl_add_u64 v[216:217], v[214:215], 0, s[12:13]
	ds_read_b128 v[174:177], v190 offset:32768
	ds_read_b128 v[178:181], v190 offset:33792
	ds_read_b128 v[182:185], v190 offset:34816
	ds_read_b128 v[192:195], v190 offset:35840
	ds_read_b128 v[196:199], v190 offset:36864
	ds_read_b128 v[200:203], v190 offset:37888
	ds_read_b128 v[204:207], v190 offset:38912
	ds_read_b128 v[208:211], v190 offset:39936
	global_load_lds_dwordx4 v[216:217], off nt
	v_lshl_add_u64 v[214:215], v[214:215], 0, s[14:15]
	s_mov_b32 m0, s60
	s_nop 0
	global_load_lds_dwordx4 v[214:215], off nt
	s_waitcnt vmcnt(8)
	s_waitcnt lgkmcnt(0)
	s_barrier
	s_setprio 1
	s_waitcnt lgkmcnt(0)
	v_mfma_f32_16x16x32_bf16 v[124:127], v[142:145], v[174:177], v[124:127]
	v_mfma_f32_16x16x32_bf16 v[124:127], v[146:149], v[178:181], v[124:127]
	v_mfma_f32_16x16x32_bf16 v[120:123], v[150:153], v[174:177], v[120:123]
	v_mfma_f32_16x16x32_bf16 v[120:123], v[154:157], v[178:181], v[120:123]
	v_mfma_f32_16x16x32_bf16 v[116:119], v[142:145], v[182:185], v[116:119]
	v_mfma_f32_16x16x32_bf16 v[116:119], v[146:149], v[192:195], v[116:119]
	v_mfma_f32_16x16x32_bf16 v[112:115], v[150:153], v[182:185], v[112:115]
	v_mfma_f32_16x16x32_bf16 v[112:115], v[154:157], v[192:195], v[112:115]
	v_mfma_f32_16x16x32_bf16 v[108:111], v[142:145], v[196:199], v[108:111]
	v_mfma_f32_16x16x32_bf16 v[108:111], v[146:149], v[200:203], v[108:111]
	v_mfma_f32_16x16x32_bf16 v[104:107], v[150:153], v[196:199], v[104:107]
	v_mfma_f32_16x16x32_bf16 v[104:107], v[154:157], v[200:203], v[104:107]
	v_mfma_f32_16x16x32_bf16 v[100:103], v[142:145], v[204:207], v[100:103]
	v_mfma_f32_16x16x32_bf16 v[100:103], v[146:149], v[208:211], v[100:103]
	v_mfma_f32_16x16x32_bf16 v[96:99], v[150:153], v[204:207], v[96:99]
	v_mfma_f32_16x16x32_bf16 v[96:99], v[154:157], v[208:211], v[96:99]
	s_setprio 0
	s_setprio 1
	v_mfma_f32_16x16x32_bf16 v[60:63], v[158:161], v[174:177], v[60:63]
	v_mfma_f32_16x16x32_bf16 v[60:63], v[162:165], v[178:181], v[60:63]
	v_mfma_f32_16x16x32_bf16 v[56:59], v[166:169], v[174:177], v[56:59]
	v_mfma_f32_16x16x32_bf16 v[56:59], v[170:173], v[178:181], v[56:59]
	v_mfma_f32_16x16x32_bf16 v[52:55], v[158:161], v[182:185], v[52:55]
	v_mfma_f32_16x16x32_bf16 v[52:55], v[162:165], v[192:195], v[52:55]
	v_mfma_f32_16x16x32_bf16 v[48:51], v[166:169], v[182:185], v[48:51]
	v_mfma_f32_16x16x32_bf16 v[48:51], v[170:173], v[192:195], v[48:51]
	v_mfma_f32_16x16x32_bf16 v[44:47], v[158:161], v[196:199], v[44:47]
	v_mfma_f32_16x16x32_bf16 v[44:47], v[162:165], v[200:203], v[44:47]
	v_mfma_f32_16x16x32_bf16 v[40:43], v[166:169], v[196:199], v[40:43]
	v_mfma_f32_16x16x32_bf16 v[40:43], v[170:173], v[200:203], v[40:43]
	v_mfma_f32_16x16x32_bf16 v[36:39], v[158:161], v[204:207], v[36:39]
	v_mfma_f32_16x16x32_bf16 v[36:39], v[162:165], v[208:211], v[36:39]
	v_mfma_f32_16x16x32_bf16 v[32:35], v[166:169], v[204:207], v[32:35]
	v_mfma_f32_16x16x32_bf16 v[32:35], v[170:173], v[208:211], v[32:35]
	s_setprio 0
	s_barrier
; #define PG8_STAGE(bufoff, gbase, voff) do { _Pragma("unroll") for (int _i = 0; _i < 2; ++_i) \
;         __builtin_amdgcn_global_load_lds((const unsigned*)((const char*)(gbase) + (size_t)_i * p##voff + (voff)), (LAS unsigned*)(lds + (bufoff) + ldsw + _i * 8192), 16, 0, 0); } while (0)
; #define PG8_LDA(dst, b, h) do { _Pragma("unroll") for (int m = 0; m < 4; ++m) _Pragma("unroll") for (int k = 0; k < 2; ++k) dst[m][k] = *(const LAS bf16x8*)(lds + PG8_SA(b, h) + aoff + m * 2048 + k * 1024); } while (0)
; #define PG8_WAIT_V(n) asm volatile("s_waitcnt vmcnt(" #n ")" ::: "memory")
; #define PG8_WAIT_L(n) asm volatile("s_waitcnt lgkmcnt(" #n ")" ::: "memory")
; #define PG8_BAR __builtin_amdgcn_s_barrier()
; #define PG8_SCHED __builtin_amdgcn_sched_barrier(0)
;     ...
;             PG8_LDA(At, 1, 1); PG8_STAGE(PG8_SB(1, 0), b3, voffB); PG8_STAGE(PG8_SB(1, 1), b3 + hstepB, voffB); PG8_STAGE(PG8_SA(1, 0), a3, voffA);
;             PG8_WAIT_V(8); PG8_WAIT_L(0); PG8_BAR; PG8_MMA(1, 0, At, B0); PG8_MMA(1, 1, At, B1); PG8_BAR; PG8_SCHED;
;         }
;     __device__ __forceinline__ void operator()(const Acc& acc, const Unit& u, int wr, int wc, int fr, int fq) const {
;     ...
;         const int rowb = u.pm * 256 + wr * 64 + fr, col0 = u.pn * 256 + wc * 32 + 8 * fq; const int b = (u.pm * 256) / S;
;         const size_t yb = (((size_t)u.pm * 16 + u.pn) * 256 + (wr * 64 + fr)) * 256 + wc * 32 + 8 * fq;
; #pragma unroll
;         for (int bj = 0; bj < 2; ++bj) {
;             f32x4 gm[2], G[2], Bc[2];
; #pragma unroll
;             for (int n = 0; n < 2; ++n) { const int c = col0 + bj * 128 + n * 4; gm[n] = *(const f32x4*)(gate + (size_t)b * NADA + c) + 1.0f; G[n] = *(const f32x4*)(lg + c) * ALPHA; Bc[n] = *(const f32x4*)(lb + c) * ALPHA; }
; #pragma unroll
;             for (int hf = 0; hf < 2; ++hf) {
;                 u32x4 yv[4]; f32x2 st[4];
; #pragma unroll
;                 for (int m = 0; m < 4; ++m) { const int row = rowb + hf * 128 + m * 16; yv[m] = *(const u32x4*)(y1 + yb + (size_t)(hf * 128 + m * 16) * 256 + bj * 128); st[m] = *(const f32x2*)(stats + (size_t)row * 2); }
	s_add_i32 s83, s83, s56
	v_lshl_add_u64 v[214:215], v[212:213], 0, s[20:21]
	s_mov_b32 m0, s83
	ds_read_b128 v[174:177], v190 offset:49152
	ds_read_b128 v[178:181], v190 offset:50176
	ds_read_b128 v[182:185], v190 offset:51200
	ds_read_b128 v[192:195], v190 offset:52224
	ds_read_b128 v[196:199], v190 offset:53248
	ds_read_b128 v[200:203], v190 offset:54272
	ds_read_b128 v[204:207], v190 offset:55296
	ds_read_b128 v[208:211], v190 offset:56320
	global_load_lds_dwordx4 v[214:215], off
	v_lshl_add_u64 v[214:215], v[212:213], 0, s[22:23]
	s_add_i32 m0, s83, 0x2000
	s_add_i32 s83, s84, s56
	global_load_lds_dwordx4 v[214:215], off
	v_lshl_add_u64 v[214:215], v[212:213], 0, s[24:25]
	s_mov_b32 m0, s83
	v_lshl_add_u64 v[212:213], v[212:213], 0, s[26:27]
	global_load_lds_dwordx4 v[214:215], off
	s_add_i32 m0, s83, 0x2000
	s_nop 0
	global_load_lds_dwordx4 v[212:213], off
	v_lshl_add_u64 v[212:213], s[50:51], 0, v[128:129]
	s_mov_b32 m0, s71
	s_nop 0
	global_load_lds_dwordx4 v[212:213], off nt
	v_lshl_add_u64 v[212:213], v[212:213], 0, s[10:11]
	s_mov_b32 m0, s72
	s_nop 0
	global_load_lds_dwordx4 v[212:213], off nt
	s_waitcnt vmcnt(8)
	s_waitcnt lgkmcnt(0)
	s_barrier
	s_setprio 1
	s_waitcnt lgkmcnt(0)
	v_mfma_f32_16x16x32_bf16 v[92:95], v[142:145], v[174:177], v[92:95]
	v_mfma_f32_16x16x32_bf16 v[92:95], v[146:149], v[178:181], v[92:95]
	v_mfma_f32_16x16x32_bf16 v[88:91], v[150:153], v[174:177], v[88:91]
	v_mfma_f32_16x16x32_bf16 v[88:91], v[154:157], v[178:181], v[88:91]
	v_mfma_f32_16x16x32_bf16 v[84:87], v[142:145], v[182:185], v[84:87]
	v_mfma_f32_16x16x32_bf16 v[84:87], v[146:149], v[192:195], v[84:87]
	v_mfma_f32_16x16x32_bf16 v[80:83], v[150:153], v[182:185], v[80:83]
	v_mfma_f32_16x16x32_bf16 v[80:83], v[154:157], v[192:195], v[80:83]
	v_mfma_f32_16x16x32_bf16 v[76:79], v[142:145], v[196:199], v[76:79]
	v_mfma_f32_16x16x32_bf16 v[76:79], v[146:149], v[200:203], v[76:79]
	v_mfma_f32_16x16x32_bf16 v[72:75], v[150:153], v[196:199], v[72:75]
	v_mfma_f32_16x16x32_bf16 v[72:75], v[154:157], v[200:203], v[72:75]
	v_mfma_f32_16x16x32_bf16 v[68:71], v[142:145], v[204:207], v[68:71]
	v_mfma_f32_16x16x32_bf16 v[68:71], v[146:149], v[208:211], v[68:71]
	v_mfma_f32_16x16x32_bf16 v[64:67], v[150:153], v[204:207], v[64:67]
	v_mfma_f32_16x16x32_bf16 v[64:67], v[154:157], v[208:211], v[64:67]
	s_setprio 0
	s_setprio 1
	v_mfma_f32_16x16x32_bf16 v[28:31], v[158:161], v[174:177], v[28:31]
	v_mfma_f32_16x16x32_bf16 v[28:31], v[162:165], v[178:181], v[28:31]
	v_mfma_f32_16x16x32_bf16 v[24:27], v[166:169], v[174:177], v[24:27]
	v_mfma_f32_16x16x32_bf16 v[24:27], v[170:173], v[178:181], v[24:27]
	v_mfma_f32_16x16x32_bf16 v[20:23], v[158:161], v[182:185], v[20:23]
	v_mfma_f32_16x16x32_bf16 v[20:23], v[162:165], v[192:195], v[20:23]
	v_mfma_f32_16x16x32_bf16 v[16:19], v[166:169], v[182:185], v[16:19]
	v_mfma_f32_16x16x32_bf16 v[16:19], v[170:173], v[192:195], v[16:19]
	v_mfma_f32_16x16x32_bf16 v[12:15], v[158:161], v[196:199], v[12:15]
	v_mfma_f32_16x16x32_bf16 v[12:15], v[162:165], v[200:203], v[12:15]
	v_mfma_f32_16x16x32_bf16 v[8:11], v[166:169], v[196:199], v[8:11]
	v_mfma_f32_16x16x32_bf16 v[8:11], v[170:173], v[200:203], v[8:11]
	v_mfma_f32_16x16x32_bf16 v[4:7], v[158:161], v[204:207], v[4:7]
	v_mfma_f32_16x16x32_bf16 v[4:7], v[162:165], v[208:211], v[4:7]
	v_mfma_f32_16x16x32_bf16 v[0:3], v[166:169], v[204:207], v[0:3]
	v_mfma_f32_16x16x32_bf16 v[0:3], v[170:173], v[208:211], v[0:3]
	s_setprio 0
	s_barrier
	s_add_i32 s82, s82, 2
	s_add_u32 s80, s80, 0x100
	s_addc_u32 s81, s81, 0
	s_add_u32 s48, s48, 0x10000
	s_addc_u32 s49, s49, 0
	s_cmpk_gt_u32 s82, 0xfd
	s_cbranch_scc0 .LBB0_1281
	s_lshl_b32 s37, s46, 8
	v_lshrrev_b32_e32 v132, 1, v191
	s_or_b32 s37, s37, s74
	v_and_b32_e32 v141, 56, v132
	s_ashr_i32 s43, s42, 31
	v_add_u32_e32 v140, s37, v141
	s_lshr_b32 s37, s43, 28
	s_lshl_b32 s35, s42, 8
	s_add_i32 s37, s42, s37
	s_ashr_i32 s47, s46, 31
	s_add_i32 s35, s35, s73
	s_ashr_i32 s37, s37, 4
	s_lshl_b64 s[42:43], s[42:43], 12
	s_lshl_b64 s[44:45], s[46:47], 8
	v_and_b32_e32 v150, 15, v191
	s_add_u32 s42, s42, s44
	s_addc_u32 s43, s43, s45
	v_or_b32_e32 v132, s73, v150
	v_lshl_add_u64 v[148:149], s[42:43], 0, v[132:133]
	s_mul_hi_i32 s43, s37, 0x18000
	s_mul_i32 s37, s37, 0x18000
	v_add_u32_e32 v132, s74, v141
	v_ashrrev_i32_e32 v141, 31, v140
	v_readlane_b32 s76, v245, 10
	s_add_u32 s42, s69, s37
	v_lshlrev_b64 v[220:221], 9, v[148:149]
	v_or_b32_e32 v154, s35, v150
	v_lshlrev_b64 v[140:141], 2, v[140:141]
	v_readlane_b32 s78, v245, 12
	v_readlane_b32 s79, v245, 13
	v_readlane_b32 s80, v245, 14
	v_readlane_b32 s81, v245, 15
	s_addc_u32 s43, s70, s43
	v_lshl_or_b32 v220, v132, 1, v220
	v_ashrrev_i32_e32 v155, 31, v154
	v_lshl_add_u64 v[142:143], s[78:79], 0, v[140:141]
	v_lshl_add_u64 v[144:145], s[80:81], 0, v[140:141]
	v_lshl_add_u64 v[146:147], s[42:43], 0, v[140:141]
	v_lshl_add_u64 v[148:149], s[16:17], 0, v[220:221]
	v_lshl_add_u64 v[140:141], v[154:155], 3, s[18:19]
	global_load_dwordx4 v[164:167], v[142:143], off offset:16
	global_load_dwordx4 v[168:171], v[142:143], off
	global_load_dwordx4 v[182:185], v[144:145], off offset:16
	global_load_dwordx4 v[192:195], v[144:145], off
	global_load_dwordx4 v[196:199], v[146:147], off offset:16
	global_load_dwordx4 v[200:203], v[146:147], off
	global_load_dwordx4 v[204:207], v[148:149], off
	global_load_dwordx2 v[222:223], v[140:141], off
	v_or_b32_e32 v152, 16, v154
	v_add_co_u32_e32 v150, vcc, s66, v148
	v_ashrrev_i32_e32 v153, 31, v152
	s_nop 0
	v_addc_co_u32_e32 v151, vcc, 0, v149, vcc
	v_lshl_add_u64 v[152:153], v[152:153], 3, s[18:19]
	global_load_dwordx4 v[208:211], v[150:151], off
	global_load_dwordx2 v[224:225], v[152:153], off
	v_add_co_u32_e32 v158, vcc, s67, v148
	v_or_b32_e32 v156, 32, v154
	s_nop 0
	v_addc_co_u32_e32 v159, vcc, 0, v149, vcc
	v_or_b32_e32 v154, 48, v154
	v_ashrrev_i32_e32 v157, 31, v156
	global_load_dwordx4 v[212:215], v[158:159], off
	v_ashrrev_i32_e32 v155, 31, v154
	v_lshl_add_u64 v[160:161], v[156:157], 3, s[18:19]
	v_add_co_u32_e32 v156, vcc, s68, v148
	v_lshl_add_u64 v[154:155], v[154:155], 3, s[18:19]
	s_nop 0
	v_addc_co_u32_e32 v157, vcc, 0, v149, vcc
	global_load_dwordx2 v[226:227], v[160:161], off
	global_load_dwordx4 v[216:219], v[156:157], off
	global_load_dwordx2 v[228:229], v[154:155], off
	v_readlane_b32 s42, v245, 61
	v_readlane_b32 s43, v245, 62
	s_mov_b32 s46, s34
	s_mov_b64 s[48:49], s[40:41]
	s_mov_b64 s[44:45], s[38:39]
	v_readlane_b32 s77, v245, 11
	v_readlane_b32 s82, v245, 16
	v_readlane_b32 s83, v245, 17
	v_readlane_b32 s84, v245, 18
	v_readlane_b32 s85, v245, 19
	v_readlane_b32 s86, v245, 20
	v_readlane_b32 s87, v245, 21
	v_readlane_b32 s88, v245, 22
	v_readlane_b32 s89, v245, 23
	v_readlane_b32 s90, v245, 24
	v_readlane_b32 s91, v245, 25
	s_waitcnt vmcnt(0)
; __device__ __forceinline__ u32x4 pack8f(f32x4 lo, f32x4 hi) { u32x4 w; w.x = cvtpk(lo[0], lo[1]); w.y = cvtpk(lo[2], lo[3]); w.z = cvtpk(hi[0], hi[1]); w.w = cvtpk(hi[2], hi[3]); return w; }
;     __device__ __forceinline__ void operator()(const Acc& acc, const Unit& u, int wr, int wc, int fr, int fq) const {
;     ...
;         for (int bj = 0; bj < 2; ++bj) {
;             f32x4 gm[2], G[2], Bc[2];
; #pragma unroll
;             for (int n = 0; n < 2; ++n) { const int c = col0 + bj * 128 + n * 4; gm[n] = *(const f32x4*)(gate + (size_t)b * NADA + c) + 1.0f; G[n] = *(const f32x4*)(lg + c) * ALPHA; Bc[n] = *(const f32x4*)(lb + c) * ALPHA; }
; #pragma unroll
;             for (int hf = 0; hf < 2; ++hf) {
;                 u32x4 yv[4]; f32x2 st[4];
; #pragma unroll
;                 for (int m = 0; m < 4; ++m) { const int row = rowb + hf * 128 + m * 16; yv[m] = *(const u32x4*)(y1 + yb + (size_t)(hf * 128 + m * 16) * 256 + bj * 128); st[m] = *(const f32x2*)(stats + (size_t)row * 2); }
; #pragma unroll
;                 for (int m = 0; m < 4; ++m) { const int row = rowb + hf * 128 + m * 16;
;                     f32x4 lo, hi; unpack8(yv[m], lo, hi); const float r = st[m][1], mr = st[m][0] * r;
;                     lo = (lo * r - mr) * G[0] + Bc[0] + gm[0] * acc[hf][bj][m][0]; hi = (hi * r - mr) * G[1] + Bc[1] + gm[1] * acc[hf][bj][m][1];
;                     *(u32x4*)(y2 + yb + (size_t)(hf * 128 + m * 16) * 256 + bj * 128) = pack8f(lo, hi); }
;                 asm volatile("" ::: "memory");
	v_pk_mul_f32 v[162:163], v[166:167], s[28:29] op_sel_hi:[1,0]
	v_pk_mul_f32 v[166:167], v[184:185], s[28:29] op_sel_hi:[1,0]
	v_pk_mul_f32 v[178:179], v[194:195], s[28:29] op_sel_hi:[1,0]
	v_pk_mul_f32 v[180:181], v[192:193], s[28:29] op_sel_hi:[1,0]
	v_pk_add_f32 v[184:185], v[200:201], 1.0 op_sel_hi:[1,0]
	v_lshlrev_b32_e32 v192, 16, v204
	v_and_b32_e32 v193, 0xffff0000, v204
	v_lshlrev_b32_e32 v194, 16, v205
	v_and_b32_e32 v195, 0xffff0000, v205
	v_pk_mul_f32 v[200:201], v[222:223], v[222:223] op_sel:[0,1] op_sel_hi:[1,0]
	v_pk_mul_f32 v[174:175], v[170:171], s[28:29] op_sel_hi:[1,0]
	v_pk_mul_f32 v[176:177], v[168:169], s[28:29] op_sel_hi:[1,0]
	v_pk_fma_f32 v[192:193], v[222:223], v[192:193], v[200:201] op_sel:[1,0,0] op_sel_hi:[1,1,0] neg_lo:[0,0,1] neg_hi:[0,0,1]
	v_pk_fma_f32 v[194:195], v[222:223], v[194:195], v[200:201] op_sel:[1,0,0] op_sel_hi:[1,1,0] neg_lo:[0,0,1] neg_hi:[0,0,1]
	v_pk_mul_f32 v[172:173], v[182:183], s[28:29] op_sel_hi:[1,0]
	v_pk_add_f32 v[182:183], v[202:203], 1.0 op_sel_hi:[1,0]
	v_pk_add_f32 v[168:169], v[198:199], 1.0 op_sel_hi:[1,0]
	v_pk_add_f32 v[170:171], v[196:197], 1.0 op_sel_hi:[1,0]
	v_lshlrev_b32_e32 v196, 16, v206
	v_and_b32_e32 v197, 0xffff0000, v206
	v_lshlrev_b32_e32 v198, 16, v207
	v_and_b32_e32 v199, 0xffff0000, v207
	v_pk_fma_f32 v[194:195], v[174:175], v[194:195], v[178:179]
	v_pk_fma_f32 v[192:193], v[176:177], v[192:193], v[180:181]
	v_pk_mul_f32 v[164:165], v[164:165], s[28:29] op_sel_hi:[1,0]
	v_pk_fma_f32 v[126:127], v[126:127], v[182:183], v[194:195]
	v_pk_fma_f32 v[124:125], v[124:125], v[184:185], v[192:193]
	v_pk_fma_f32 v[192:193], v[222:223], v[196:197], v[200:201] op_sel:[1,0,0] op_sel_hi:[1,1,0] neg_lo:[0,0,1] neg_hi:[0,0,1]
	v_pk_fma_f32 v[194:195], v[222:223], v[198:199], v[200:201] op_sel:[1,0,0] op_sel_hi:[1,1,0] neg_lo:[0,0,1] neg_hi:[0,0,1]
	v_pk_fma_f32 v[192:193], v[164:165], v[192:193], v[172:173]
	v_pk_fma_f32 v[194:195], v[162:163], v[194:195], v[166:167]
	v_pk_fma_f32 v[120:121], v[120:121], v[170:171], v[192:193]
	v_pk_fma_f32 v[194:195], v[122:123], v[168:169], v[194:195]
	v_cvt_pk_bf16_f32 v122, v124, v125
	v_cvt_pk_bf16_f32 v123, v126, v127
	v_cvt_pk_bf16_f32 v124, v120, v121
	v_cvt_pk_bf16_f32 v125, v194, v195
	v_lshl_add_u64 v[120:121], s[42:43], 0, v[220:221]
	global_store_dwordx4 v[120:121], v[122:125], off
	v_pk_mul_f32 v[194:195], v[224:225], v[224:225] op_sel:[0,1] op_sel_hi:[1,0]
	v_lshlrev_b32_e32 v126, 16, v210
	v_lshlrev_b32_e32 v124, 16, v209
	v_and_b32_e32 v125, 0xffff0000, v209
	v_lshlrev_b32_e32 v122, 16, v208
	v_and_b32_e32 v123, 0xffff0000, v208
	v_pk_fma_f32 v[124:125], v[224:225], v[124:125], v[194:195] op_sel:[1,0,0] op_sel_hi:[1,1,0] neg_lo:[0,0,1] neg_hi:[0,0,1]
	v_and_b32_e32 v127, 0xffff0000, v210
	v_pk_fma_f32 v[122:123], v[224:225], v[122:123], v[194:195] op_sel:[1,0,0] op_sel_hi:[1,1,0] neg_lo:[0,0,1] neg_hi:[0,0,1]
	v_pk_fma_f32 v[124:125], v[174:175], v[124:125], v[178:179]
	v_lshlrev_b32_e32 v192, 16, v211
	v_and_b32_e32 v193, 0xffff0000, v211
	v_pk_fma_f32 v[122:123], v[176:177], v[122:123], v[180:181]
	v_pk_fma_f32 v[118:119], v[118:119], v[182:183], v[124:125]
	v_pk_fma_f32 v[124:125], v[224:225], v[126:127], v[194:195] op_sel:[1,0,0] op_sel_hi:[1,1,0] neg_lo:[0,0,1] neg_hi:[0,0,1]
	v_pk_fma_f32 v[116:117], v[116:117], v[184:185], v[122:123]
	v_pk_fma_f32 v[122:123], v[224:225], v[192:193], v[194:195] op_sel:[1,0,0] op_sel_hi:[1,1,0] neg_lo:[0,0,1] neg_hi:[0,0,1]
	v_pk_fma_f32 v[124:125], v[164:165], v[124:125], v[172:173]
	v_pk_fma_f32 v[122:123], v[162:163], v[122:123], v[166:167]
	v_pk_fma_f32 v[112:113], v[112:113], v[170:171], v[124:125]
	v_pk_fma_f32 v[122:123], v[114:115], v[168:169], v[122:123]
	v_cvt_pk_bf16_f32 v114, v116, v117
	v_cvt_pk_bf16_f32 v116, v112, v113
	v_add_co_u32_e32 v112, vcc, s66, v120
	v_cvt_pk_bf16_f32 v115, v118, v119
	v_cvt_pk_bf16_f32 v117, v122, v123
	v_addc_co_u32_e32 v113, vcc, 0, v121, vcc
	global_store_dwordx4 v[112:113], v[114:117], off
	v_pk_mul_f32 v[124:125], v[226:227], v[226:227] op_sel:[0,1] op_sel_hi:[1,0]
	v_lshlrev_b32_e32 v118, 16, v214
	v_lshlrev_b32_e32 v116, 16, v213
	v_and_b32_e32 v117, 0xffff0000, v213
	v_lshlrev_b32_e32 v114, 16, v212
	v_and_b32_e32 v115, 0xffff0000, v212
	v_pk_fma_f32 v[116:117], v[226:227], v[116:117], v[124:125] op_sel:[1,0,0] op_sel_hi:[1,1,0] neg_lo:[0,0,1] neg_hi:[0,0,1]
	v_and_b32_e32 v119, 0xffff0000, v214
	v_pk_fma_f32 v[114:115], v[226:227], v[114:115], v[124:125] op_sel:[1,0,0] op_sel_hi:[1,1,0] neg_lo:[0,0,1] neg_hi:[0,0,1]
	v_pk_fma_f32 v[116:117], v[174:175], v[116:117], v[178:179]
	v_lshlrev_b32_e32 v122, 16, v215
	v_and_b32_e32 v123, 0xffff0000, v215
	v_pk_fma_f32 v[114:115], v[176:177], v[114:115], v[180:181]
	v_pk_fma_f32 v[110:111], v[110:111], v[182:183], v[116:117]
	v_pk_fma_f32 v[116:117], v[226:227], v[118:119], v[124:125] op_sel:[1,0,0] op_sel_hi:[1,1,0] neg_lo:[0,0,1] neg_hi:[0,0,1]
	v_pk_fma_f32 v[108:109], v[108:109], v[184:185], v[114:115]
	v_pk_fma_f32 v[114:115], v[226:227], v[122:123], v[124:125] op_sel:[1,0,0] op_sel_hi:[1,1,0] neg_lo:[0,0,1] neg_hi:[0,0,1]
	v_pk_fma_f32 v[116:117], v[164:165], v[116:117], v[172:173]
	v_pk_fma_f32 v[114:115], v[162:163], v[114:115], v[166:167]
	v_pk_fma_f32 v[104:105], v[104:105], v[170:171], v[116:117]
	v_pk_fma_f32 v[114:115], v[106:107], v[168:169], v[114:115]
	v_cvt_pk_bf16_f32 v106, v108, v109
	v_cvt_pk_bf16_f32 v108, v104, v105
	v_add_co_u32_e32 v104, vcc, s67, v120
	v_cvt_pk_bf16_f32 v107, v110, v111
	v_cvt_pk_bf16_f32 v109, v114, v115
	v_addc_co_u32_e32 v105, vcc, 0, v121, vcc
	global_store_dwordx4 v[104:105], v[106:109], off
	v_pk_mul_f32 v[116:117], v[228:229], v[228:229] op_sel:[0,1] op_sel_hi:[1,0]
; __device__ __forceinline__ u32x4 pack8f(f32x4 lo, f32x4 hi) { u32x4 w; w.x = cvtpk(lo[0], lo[1]); w.y = cvtpk(lo[2], lo[3]); w.z = cvtpk(hi[0], hi[1]); w.w = cvtpk(hi[2], hi[3]); return w; }
;     __device__ __forceinline__ void operator()(const Acc& acc, const Unit& u, int wr, int wc, int fr, int fq) const {
;     ...
;             for (int hf = 0; hf < 2; ++hf) {
;                 u32x4 yv[4]; f32x2 st[4];
; #pragma unroll
;                 for (int m = 0; m < 4; ++m) { const int row = rowb + hf * 128 + m * 16; yv[m] = *(const u32x4*)(y1 + yb + (size_t)(hf * 128 + m * 16) * 256 + bj * 128); st[m] = *(const f32x2*)(stats + (size_t)row * 2); }
; #pragma unroll
;                 for (int m = 0; m < 4; ++m) { const int row = rowb + hf * 128 + m * 16;
;                     f32x4 lo, hi; unpack8(yv[m], lo, hi); const float r = st[m][1], mr = st[m][0] * r;
;                     lo = (lo * r - mr) * G[0] + Bc[0] + gm[0] * acc[hf][bj][m][0]; hi = (hi * r - mr) * G[1] + Bc[1] + gm[1] * acc[hf][bj][m][1];
;                     *(u32x4*)(y2 + yb + (size_t)(hf * 128 + m * 16) * 256 + bj * 128) = pack8f(lo, hi); }
;                 asm volatile("" ::: "memory");
	v_lshlrev_b32_e32 v110, 16, v218
	v_lshlrev_b32_e32 v108, 16, v217
	v_and_b32_e32 v109, 0xffff0000, v217
	v_lshlrev_b32_e32 v106, 16, v216
	v_and_b32_e32 v107, 0xffff0000, v216
	v_pk_fma_f32 v[108:109], v[228:229], v[108:109], v[116:117] op_sel:[1,0,0] op_sel_hi:[1,1,0] neg_lo:[0,0,1] neg_hi:[0,0,1]
	v_and_b32_e32 v111, 0xffff0000, v218
	v_pk_fma_f32 v[106:107], v[228:229], v[106:107], v[116:117] op_sel:[1,0,0] op_sel_hi:[1,1,0] neg_lo:[0,0,1] neg_hi:[0,0,1]
	v_pk_fma_f32 v[108:109], v[174:175], v[108:109], v[178:179]
	v_lshlrev_b32_e32 v114, 16, v219
	v_and_b32_e32 v115, 0xffff0000, v219
	v_pk_fma_f32 v[106:107], v[176:177], v[106:107], v[180:181]
	v_pk_fma_f32 v[102:103], v[102:103], v[182:183], v[108:109]
	v_pk_fma_f32 v[108:109], v[228:229], v[110:111], v[116:117] op_sel:[1,0,0] op_sel_hi:[1,1,0] neg_lo:[0,0,1] neg_hi:[0,0,1]
	v_pk_fma_f32 v[100:101], v[100:101], v[184:185], v[106:107]
	v_pk_fma_f32 v[106:107], v[228:229], v[114:115], v[116:117] op_sel:[1,0,0] op_sel_hi:[1,1,0] neg_lo:[0,0,1] neg_hi:[0,0,1]
	v_pk_fma_f32 v[108:109], v[164:165], v[108:109], v[172:173]
	v_pk_fma_f32 v[106:107], v[162:163], v[106:107], v[166:167]
	v_pk_fma_f32 v[96:97], v[96:97], v[170:171], v[108:109]
	v_pk_fma_f32 v[106:107], v[98:99], v[168:169], v[106:107]
	v_cvt_pk_bf16_f32 v98, v100, v101
	v_cvt_pk_bf16_f32 v100, v96, v97
	v_add_co_u32_e32 v96, vcc, s68, v120
	v_cvt_pk_bf16_f32 v99, v102, v103
	v_cvt_pk_bf16_f32 v101, v106, v107
	v_addc_co_u32_e32 v97, vcc, 0, v121, vcc
	global_store_dwordx4 v[96:97], v[98:101], off
	s_mov_b32 s42, s36
	s_nop 0
	v_add_co_u32_e32 v98, vcc, s62, v148
	s_nop 1
	v_addc_co_u32_e32 v99, vcc, 0, v149, vcc
	global_load_dwordx4 v[108:111], v[98:99], off
	global_load_dwordx2 v[118:119], v[140:141], off offset:1024
	v_add_co_u32_e32 v100, vcc, s63, v148
	s_waitcnt vmcnt(1)
	v_lshlrev_b32_e32 v200, 16, v108
	v_addc_co_u32_e32 v101, vcc, 0, v149, vcc
	global_load_dwordx4 v[114:117], v[100:101], off
	global_load_dwordx2 v[126:127], v[140:141], off offset:1152
	v_add_co_u32_e32 v102, vcc, s64, v148
	v_and_b32_e32 v201, 0xffff0000, v108
	s_nop 0
	v_addc_co_u32_e32 v103, vcc, 0, v149, vcc
	global_load_dwordx4 v[122:125], v[102:103], off
	global_load_dwordx2 v[196:197], v[140:141], off offset:1280
	v_add_co_u32_e32 v106, vcc, s65, v148
	v_lshlrev_b32_e32 v108, 16, v109
	s_nop 0
	v_addc_co_u32_e32 v107, vcc, 0, v149, vcc
	global_load_dwordx4 v[192:195], v[106:107], off
	global_load_dwordx2 v[198:199], v[140:141], off offset:1408
	v_and_b32_e32 v109, 0xffff0000, v109
	s_waitcnt vmcnt(6)
	v_pk_mul_f32 v[204:205], v[118:119], v[118:119] op_sel:[0,1] op_sel_hi:[1,0]
	v_lshlrev_b32_e32 v202, 16, v110
	v_pk_fma_f32 v[108:109], v[118:119], v[108:109], v[204:205] op_sel:[1,0,0] op_sel_hi:[1,1,0] neg_lo:[0,0,1] neg_hi:[0,0,1]
	v_and_b32_e32 v203, 0xffff0000, v110
	v_lshlrev_b32_e32 v110, 16, v111
	v_and_b32_e32 v111, 0xffff0000, v111
	v_pk_fma_f32 v[108:109], v[174:175], v[108:109], v[178:179]
	v_pk_fma_f32 v[200:201], v[118:119], v[200:201], v[204:205] op_sel:[1,0,0] op_sel_hi:[1,1,0] neg_lo:[0,0,1] neg_hi:[0,0,1]
	v_pk_fma_f32 v[94:95], v[94:95], v[182:183], v[108:109]
	v_pk_fma_f32 v[108:109], v[118:119], v[110:111], v[204:205] op_sel:[1,0,0] op_sel_hi:[1,1,0] neg_lo:[0,0,1] neg_hi:[0,0,1]
	v_pk_fma_f32 v[110:111], v[118:119], v[202:203], v[204:205] op_sel:[1,0,0] op_sel_hi:[1,1,0] neg_lo:[0,0,1] neg_hi:[0,0,1]
	v_pk_fma_f32 v[200:201], v[176:177], v[200:201], v[180:181]
	v_pk_fma_f32 v[110:111], v[164:165], v[110:111], v[172:173]
	v_pk_fma_f32 v[92:93], v[92:93], v[184:185], v[200:201]
	v_pk_fma_f32 v[108:109], v[162:163], v[108:109], v[166:167]
	v_pk_fma_f32 v[88:89], v[88:89], v[170:171], v[110:111]
	v_pk_fma_f32 v[108:109], v[90:91], v[168:169], v[108:109]
	v_cvt_pk_bf16_f32 v90, v92, v93
	v_cvt_pk_bf16_f32 v92, v88, v89
	v_add_co_u32_e32 v88, vcc, s62, v120
	v_cvt_pk_bf16_f32 v91, v94, v95
	v_cvt_pk_bf16_f32 v93, v108, v109
	v_addc_co_u32_e32 v89, vcc, 0, v121, vcc
	global_store_dwordx4 v[88:89], v[90:93], off
	s_waitcnt vmcnt(6)
	v_lshlrev_b32_e32 v94, 16, v116
	v_lshlrev_b32_e32 v92, 16, v115
	v_and_b32_e32 v93, 0xffff0000, v115
	s_waitcnt vmcnt(5)
	v_pk_mul_f32 v[110:111], v[126:127], v[126:127] op_sel:[0,1] op_sel_hi:[1,0]
	v_lshlrev_b32_e32 v90, 16, v114
	v_and_b32_e32 v91, 0xffff0000, v114
	v_pk_fma_f32 v[92:93], v[126:127], v[92:93], v[110:111] op_sel:[1,0,0] op_sel_hi:[1,1,0] neg_lo:[0,0,1] neg_hi:[0,0,1]
	v_and_b32_e32 v95, 0xffff0000, v116
	v_pk_fma_f32 v[90:91], v[126:127], v[90:91], v[110:111] op_sel:[1,0,0] op_sel_hi:[1,1,0] neg_lo:[0,0,1] neg_hi:[0,0,1]
	v_pk_fma_f32 v[92:93], v[174:175], v[92:93], v[178:179]
	v_lshlrev_b32_e32 v108, 16, v117
	v_and_b32_e32 v109, 0xffff0000, v117
	v_pk_fma_f32 v[90:91], v[176:177], v[90:91], v[180:181]
	v_pk_fma_f32 v[86:87], v[86:87], v[182:183], v[92:93]
	v_pk_fma_f32 v[92:93], v[126:127], v[94:95], v[110:111] op_sel:[1,0,0] op_sel_hi:[1,1,0] neg_lo:[0,0,1] neg_hi:[0,0,1]
	v_pk_fma_f32 v[84:85], v[84:85], v[184:185], v[90:91]
	v_pk_fma_f32 v[90:91], v[126:127], v[108:109], v[110:111] op_sel:[1,0,0] op_sel_hi:[1,1,0] neg_lo:[0,0,1] neg_hi:[0,0,1]
	v_pk_fma_f32 v[92:93], v[164:165], v[92:93], v[172:173]
	v_pk_fma_f32 v[90:91], v[162:163], v[90:91], v[166:167]
	v_pk_fma_f32 v[80:81], v[80:81], v[170:171], v[92:93]
	v_pk_fma_f32 v[90:91], v[82:83], v[168:169], v[90:91]
	v_cvt_pk_bf16_f32 v82, v84, v85
	v_cvt_pk_bf16_f32 v84, v80, v81
	v_add_co_u32_e32 v80, vcc, s63, v120
	v_cvt_pk_bf16_f32 v83, v86, v87
	v_cvt_pk_bf16_f32 v85, v90, v91
	v_addc_co_u32_e32 v81, vcc, 0, v121, vcc
	global_store_dwordx4 v[80:81], v[82:85], off
	s_waitcnt vmcnt(4)
; __device__ __forceinline__ u32x4 pack8f(f32x4 lo, f32x4 hi) { u32x4 w; w.x = cvtpk(lo[0], lo[1]); w.y = cvtpk(lo[2], lo[3]); w.z = cvtpk(hi[0], hi[1]); w.w = cvtpk(hi[2], hi[3]); return w; }
;     __device__ __forceinline__ void operator()(const Acc& acc, const Unit& u, int wr, int wc, int fr, int fq) const {
;     ...
;         for (int bj = 0; bj < 2; ++bj) {
;             f32x4 gm[2], G[2], Bc[2];
; #pragma unroll
;             for (int n = 0; n < 2; ++n) { const int c = col0 + bj * 128 + n * 4; gm[n] = *(const f32x4*)(gate + (size_t)b * NADA + c) + 1.0f; G[n] = *(const f32x4*)(lg + c) * ALPHA; Bc[n] = *(const f32x4*)(lb + c) * ALPHA; }
; #pragma unroll
;             for (int hf = 0; hf < 2; ++hf) {
;                 u32x4 yv[4]; f32x2 st[4];
; #pragma unroll
;                 for (int m = 0; m < 4; ++m) { const int row = rowb + hf * 128 + m * 16; yv[m] = *(const u32x4*)(y1 + yb + (size_t)(hf * 128 + m * 16) * 256 + bj * 128); st[m] = *(const f32x2*)(stats + (size_t)row * 2); }
; #pragma unroll
;                 for (int m = 0; m < 4; ++m) { const int row = rowb + hf * 128 + m * 16;
;                     f32x4 lo, hi; unpack8(yv[m], lo, hi); const float r = st[m][1], mr = st[m][0] * r;
;                     lo = (lo * r - mr) * G[0] + Bc[0] + gm[0] * acc[hf][bj][m][0]; hi = (hi * r - mr) * G[1] + Bc[1] + gm[1] * acc[hf][bj][m][1];
;                     *(u32x4*)(y2 + yb + (size_t)(hf * 128 + m * 16) * 256 + bj * 128) = pack8f(lo, hi); }
;                 asm volatile("" ::: "memory");
	v_pk_mul_f32 v[92:93], v[196:197], v[196:197] op_sel:[0,1] op_sel_hi:[1,0]
	v_lshlrev_b32_e32 v86, 16, v124
	v_lshlrev_b32_e32 v84, 16, v123
	v_and_b32_e32 v85, 0xffff0000, v123
	v_lshlrev_b32_e32 v82, 16, v122
	v_and_b32_e32 v83, 0xffff0000, v122
	v_pk_fma_f32 v[84:85], v[196:197], v[84:85], v[92:93] op_sel:[1,0,0] op_sel_hi:[1,1,0] neg_lo:[0,0,1] neg_hi:[0,0,1]
	v_and_b32_e32 v87, 0xffff0000, v124
	v_pk_fma_f32 v[82:83], v[196:197], v[82:83], v[92:93] op_sel:[1,0,0] op_sel_hi:[1,1,0] neg_lo:[0,0,1] neg_hi:[0,0,1]
	v_pk_fma_f32 v[84:85], v[174:175], v[84:85], v[178:179]
	v_lshlrev_b32_e32 v90, 16, v125
	v_and_b32_e32 v91, 0xffff0000, v125
	v_pk_fma_f32 v[82:83], v[176:177], v[82:83], v[180:181]
	v_pk_fma_f32 v[78:79], v[78:79], v[182:183], v[84:85]
	v_pk_fma_f32 v[84:85], v[196:197], v[86:87], v[92:93] op_sel:[1,0,0] op_sel_hi:[1,1,0] neg_lo:[0,0,1] neg_hi:[0,0,1]
	v_pk_fma_f32 v[76:77], v[76:77], v[184:185], v[82:83]
	v_pk_fma_f32 v[82:83], v[196:197], v[90:91], v[92:93] op_sel:[1,0,0] op_sel_hi:[1,1,0] neg_lo:[0,0,1] neg_hi:[0,0,1]
	v_pk_fma_f32 v[84:85], v[164:165], v[84:85], v[172:173]
	v_pk_fma_f32 v[82:83], v[162:163], v[82:83], v[166:167]
	v_pk_fma_f32 v[72:73], v[72:73], v[170:171], v[84:85]
	v_pk_fma_f32 v[82:83], v[74:75], v[168:169], v[82:83]
	v_cvt_pk_bf16_f32 v74, v76, v77
	v_cvt_pk_bf16_f32 v76, v72, v73
	v_add_co_u32_e32 v72, vcc, s64, v120
	v_cvt_pk_bf16_f32 v75, v78, v79
	v_cvt_pk_bf16_f32 v77, v82, v83
	v_addc_co_u32_e32 v73, vcc, 0, v121, vcc
	global_store_dwordx4 v[72:73], v[74:77], off
	s_waitcnt vmcnt(3)
	v_pk_mul_f32 v[84:85], v[198:199], v[198:199] op_sel:[0,1] op_sel_hi:[1,0]
	v_lshlrev_b32_e32 v78, 16, v194
	v_lshlrev_b32_e32 v76, 16, v193
	v_and_b32_e32 v77, 0xffff0000, v193
	v_lshlrev_b32_e32 v74, 16, v192
	v_and_b32_e32 v75, 0xffff0000, v192
	v_pk_fma_f32 v[76:77], v[198:199], v[76:77], v[84:85] op_sel:[1,0,0] op_sel_hi:[1,1,0] neg_lo:[0,0,1] neg_hi:[0,0,1]
	v_and_b32_e32 v79, 0xffff0000, v194
	v_pk_fma_f32 v[74:75], v[198:199], v[74:75], v[84:85] op_sel:[1,0,0] op_sel_hi:[1,1,0] neg_lo:[0,0,1] neg_hi:[0,0,1]
	v_pk_fma_f32 v[76:77], v[174:175], v[76:77], v[178:179]
	v_lshlrev_b32_e32 v82, 16, v195
	v_and_b32_e32 v83, 0xffff0000, v195
	v_pk_fma_f32 v[74:75], v[176:177], v[74:75], v[180:181]
	v_pk_fma_f32 v[70:71], v[70:71], v[182:183], v[76:77]
	v_pk_fma_f32 v[76:77], v[198:199], v[78:79], v[84:85] op_sel:[1,0,0] op_sel_hi:[1,1,0] neg_lo:[0,0,1] neg_hi:[0,0,1]
	v_pk_fma_f32 v[68:69], v[68:69], v[184:185], v[74:75]
	v_pk_fma_f32 v[74:75], v[198:199], v[82:83], v[84:85] op_sel:[1,0,0] op_sel_hi:[1,1,0] neg_lo:[0,0,1] neg_hi:[0,0,1]
	v_pk_fma_f32 v[76:77], v[164:165], v[76:77], v[172:173]
	v_pk_fma_f32 v[74:75], v[162:163], v[74:75], v[166:167]
	v_pk_fma_f32 v[64:65], v[64:65], v[170:171], v[76:77]
	v_pk_fma_f32 v[74:75], v[66:67], v[168:169], v[74:75]
	v_cvt_pk_bf16_f32 v66, v68, v69
	v_cvt_pk_bf16_f32 v68, v64, v65
	v_add_co_u32_e32 v64, vcc, s65, v120
	v_cvt_pk_bf16_f32 v67, v70, v71
	v_cvt_pk_bf16_f32 v69, v74, v75
	v_addc_co_u32_e32 v65, vcc, 0, v121, vcc
	global_store_dwordx4 v[64:65], v[66:69], off
	global_load_dwordx4 v[66:69], v[146:147], off offset:512
	global_load_dwordx4 v[82:85], v[142:143], off offset:512
	global_load_dwordx4 v[108:111], v[144:145], off offset:512
	global_load_dwordx4 v[114:117], v[146:147], off offset:528
	global_load_dwordx4 v[122:125], v[142:143], off offset:528
	s_nop 0
	global_load_dwordx4 v[142:145], v[144:145], off offset:528
	s_nop 0
	global_load_dwordx4 v[146:149], v[148:149], off offset:256
	s_nop 0
	global_load_dwordx2 v[118:119], v[140:141], off
	global_load_dwordx4 v[162:165], v[150:151], off offset:256
	global_load_dwordx2 v[126:127], v[152:153], off
	s_nop 0
	global_load_dwordx4 v[150:153], v[158:159], off offset:256
	s_nop 0
	global_load_dwordx2 v[158:159], v[160:161], off
	s_and_b64 vcc, exec, s[2:3]
	s_waitcnt vmcnt(11)
	v_pk_add_f32 v[74:75], v[68:69], 1.0 op_sel_hi:[1,0]
	v_pk_add_f32 v[76:77], v[66:67], 1.0 op_sel_hi:[1,0]
	s_waitcnt vmcnt(9)
	v_pk_mul_f32 v[92:93], v[110:111], s[28:29] op_sel_hi:[1,0]
	v_pk_mul_f32 v[94:95], v[108:109], s[28:29] op_sel_hi:[1,0]
	s_waitcnt vmcnt(8)
	v_pk_add_f32 v[68:69], v[114:115], 1.0 op_sel_hi:[1,0]
	global_load_dwordx4 v[108:111], v[156:157], off offset:256
	global_load_dwordx2 v[114:115], v[154:155], off
	v_pk_mul_f32 v[90:91], v[82:83], s[28:29] op_sel_hi:[1,0]
	v_pk_add_f32 v[66:67], v[116:117], 1.0 op_sel_hi:[1,0]
	s_waitcnt vmcnt(8)
	v_pk_mul_f32 v[82:83], v[144:145], s[28:29] op_sel_hi:[1,0]
	s_waitcnt vmcnt(7)
	v_lshlrev_b32_e32 v116, 16, v146
	v_and_b32_e32 v117, 0xffff0000, v146
	s_waitcnt vmcnt(6)
	v_pk_mul_f32 v[144:145], v[118:119], v[118:119] op_sel:[0,1] op_sel_hi:[1,0]
	v_pk_mul_f32 v[86:87], v[84:85], s[28:29] op_sel_hi:[1,0]
	v_pk_fma_f32 v[116:117], v[118:119], v[116:117], v[144:145] op_sel:[1,0,0] op_sel_hi:[1,1,0] neg_lo:[0,0,1] neg_hi:[0,0,1]
	v_pk_mul_f32 v[70:71], v[124:125], s[28:29] op_sel_hi:[1,0]
	v_pk_mul_f32 v[78:79], v[122:123], s[28:29] op_sel_hi:[1,0]
	v_pk_mul_f32 v[84:85], v[142:143], s[28:29] op_sel_hi:[1,0]
	v_lshlrev_b32_e32 v122, 16, v147
	v_and_b32_e32 v123, 0xffff0000, v147
	v_lshlrev_b32_e32 v124, 16, v148
	v_and_b32_e32 v125, 0xffff0000, v148
	v_lshlrev_b32_e32 v142, 16, v149
	v_and_b32_e32 v143, 0xffff0000, v149
	v_pk_fma_f32 v[116:117], v[90:91], v[116:117], v[94:95]
	v_pk_fma_f32 v[122:123], v[118:119], v[122:123], v[144:145] op_sel:[1,0,0] op_sel_hi:[1,1,0] neg_lo:[0,0,1] neg_hi:[0,0,1]
	v_pk_fma_f32 v[60:61], v[60:61], v[76:77], v[116:117]
	v_pk_fma_f32 v[116:117], v[118:119], v[124:125], v[144:145] op_sel:[1,0,0] op_sel_hi:[1,1,0] neg_lo:[0,0,1] neg_hi:[0,0,1]
	v_pk_fma_f32 v[118:119], v[118:119], v[142:143], v[144:145] op_sel:[1,0,0] op_sel_hi:[1,1,0] neg_lo:[0,0,1] neg_hi:[0,0,1]
	v_pk_fma_f32 v[122:123], v[86:87], v[122:123], v[92:93]
	v_pk_fma_f32 v[118:119], v[70:71], v[118:119], v[82:83]
	v_pk_fma_f32 v[116:117], v[78:79], v[116:117], v[84:85]
	v_pk_fma_f32 v[62:63], v[62:63], v[74:75], v[122:123]
	v_pk_fma_f32 v[118:119], v[58:59], v[66:67], v[118:119]
	v_pk_fma_f32 v[58:59], v[56:57], v[68:69], v[116:117]
	v_cvt_pk_bf16_f32 v56, v60, v61
	v_cvt_pk_bf16_f32 v57, v62, v63
	v_cvt_pk_bf16_f32 v58, v58, v59
	v_cvt_pk_bf16_f32 v59, v118, v119
	global_store_dwordx4 v[120:121], v[56:59], off offset:256
	s_waitcnt vmcnt(5)
; __device__ __forceinline__ u32x4 pack8f(f32x4 lo, f32x4 hi) { u32x4 w; w.x = cvtpk(lo[0], lo[1]); w.y = cvtpk(lo[2], lo[3]); w.z = cvtpk(hi[0], hi[1]); w.w = cvtpk(hi[2], hi[3]); return w; }
;     __device__ __forceinline__ void operator()(const Acc& acc, const Unit& u, int wr, int wc, int fr, int fq) const {
;     ...
;         for (int bj = 0; bj < 2; ++bj) {
;             f32x4 gm[2], G[2], Bc[2];
; #pragma unroll
;             for (int n = 0; n < 2; ++n) { const int c = col0 + bj * 128 + n * 4; gm[n] = *(const f32x4*)(gate + (size_t)b * NADA + c) + 1.0f; G[n] = *(const f32x4*)(lg + c) * ALPHA; Bc[n] = *(const f32x4*)(lb + c) * ALPHA; }
; #pragma unroll
;             for (int hf = 0; hf < 2; ++hf) {
;                 u32x4 yv[4]; f32x2 st[4];
; #pragma unroll
;                 for (int m = 0; m < 4; ++m) { const int row = rowb + hf * 128 + m * 16; yv[m] = *(const u32x4*)(y1 + yb + (size_t)(hf * 128 + m * 16) * 256 + bj * 128); st[m] = *(const f32x2*)(stats + (size_t)row * 2); }
; #pragma unroll
;                 for (int m = 0; m < 4; ++m) { const int row = rowb + hf * 128 + m * 16;
;                     f32x4 lo, hi; unpack8(yv[m], lo, hi); const float r = st[m][1], mr = st[m][0] * r;
;                     lo = (lo * r - mr) * G[0] + Bc[0] + gm[0] * acc[hf][bj][m][0]; hi = (hi * r - mr) * G[1] + Bc[1] + gm[1] * acc[hf][bj][m][1];
;                     *(u32x4*)(y2 + yb + (size_t)(hf * 128 + m * 16) * 256 + bj * 128) = pack8f(lo, hi); }
;                 asm volatile("" ::: "memory");
	v_pk_mul_f32 v[116:117], v[126:127], v[126:127] op_sel:[0,1] op_sel_hi:[1,0]
	v_lshlrev_b32_e32 v60, 16, v164
	v_lshlrev_b32_e32 v56, 16, v162
	v_and_b32_e32 v57, 0xffff0000, v162
	v_lshlrev_b32_e32 v58, 16, v163
	v_and_b32_e32 v59, 0xffff0000, v163
	v_pk_fma_f32 v[58:59], v[126:127], v[58:59], v[116:117] op_sel:[1,0,0] op_sel_hi:[1,1,0] neg_lo:[0,0,1] neg_hi:[0,0,1]
	v_pk_fma_f32 v[56:57], v[126:127], v[56:57], v[116:117] op_sel:[1,0,0] op_sel_hi:[1,1,0] neg_lo:[0,0,1] neg_hi:[0,0,1]
	v_and_b32_e32 v61, 0xffff0000, v164
	v_lshlrev_b32_e32 v62, 16, v165
	v_and_b32_e32 v63, 0xffff0000, v165
	v_pk_fma_f32 v[56:57], v[90:91], v[56:57], v[94:95]
	v_pk_fma_f32 v[58:59], v[86:87], v[58:59], v[92:93]
	v_pk_fma_f32 v[52:53], v[52:53], v[76:77], v[56:57]
	v_pk_fma_f32 v[54:55], v[54:55], v[74:75], v[58:59]
	v_pk_fma_f32 v[56:57], v[126:127], v[62:63], v[116:117] op_sel:[1,0,0] op_sel_hi:[1,1,0] neg_lo:[0,0,1] neg_hi:[0,0,1]
	v_pk_fma_f32 v[58:59], v[126:127], v[60:61], v[116:117] op_sel:[1,0,0] op_sel_hi:[1,1,0] neg_lo:[0,0,1] neg_hi:[0,0,1]
	v_pk_fma_f32 v[56:57], v[70:71], v[56:57], v[82:83]
	v_pk_fma_f32 v[58:59], v[78:79], v[58:59], v[84:85]
	v_pk_fma_f32 v[56:57], v[50:51], v[66:67], v[56:57]
	v_pk_fma_f32 v[50:51], v[48:49], v[68:69], v[58:59]
	v_cvt_pk_bf16_f32 v48, v52, v53
	v_cvt_pk_bf16_f32 v49, v54, v55
	v_cvt_pk_bf16_f32 v50, v50, v51
	v_cvt_pk_bf16_f32 v51, v56, v57
	global_store_dwordx4 v[112:113], v[48:51], off offset:256
	s_waitcnt vmcnt(4)
	v_pk_mul_f32 v[56:57], v[158:159], v[158:159] op_sel:[0,1] op_sel_hi:[1,0]
	v_lshlrev_b32_e32 v52, 16, v152
	v_lshlrev_b32_e32 v48, 16, v150
	v_and_b32_e32 v49, 0xffff0000, v150
	v_lshlrev_b32_e32 v50, 16, v151
	v_and_b32_e32 v51, 0xffff0000, v151
	v_pk_fma_f32 v[50:51], v[158:159], v[50:51], v[56:57] op_sel:[1,0,0] op_sel_hi:[1,1,0] neg_lo:[0,0,1] neg_hi:[0,0,1]
	v_pk_fma_f32 v[48:49], v[158:159], v[48:49], v[56:57] op_sel:[1,0,0] op_sel_hi:[1,1,0] neg_lo:[0,0,1] neg_hi:[0,0,1]
	v_and_b32_e32 v53, 0xffff0000, v152
	v_lshlrev_b32_e32 v54, 16, v153
	v_and_b32_e32 v55, 0xffff0000, v153
	v_pk_fma_f32 v[48:49], v[90:91], v[48:49], v[94:95]
	v_pk_fma_f32 v[50:51], v[86:87], v[50:51], v[92:93]
	v_pk_fma_f32 v[44:45], v[44:45], v[76:77], v[48:49]
	v_pk_fma_f32 v[46:47], v[46:47], v[74:75], v[50:51]
	v_pk_fma_f32 v[48:49], v[158:159], v[54:55], v[56:57] op_sel:[1,0,0] op_sel_hi:[1,1,0] neg_lo:[0,0,1] neg_hi:[0,0,1]
	v_pk_fma_f32 v[50:51], v[158:159], v[52:53], v[56:57] op_sel:[1,0,0] op_sel_hi:[1,1,0] neg_lo:[0,0,1] neg_hi:[0,0,1]
	v_pk_fma_f32 v[48:49], v[70:71], v[48:49], v[82:83]
	v_pk_fma_f32 v[50:51], v[78:79], v[50:51], v[84:85]
	v_pk_fma_f32 v[48:49], v[42:43], v[66:67], v[48:49]
	v_pk_fma_f32 v[42:43], v[40:41], v[68:69], v[50:51]
	v_cvt_pk_bf16_f32 v40, v44, v45
	v_cvt_pk_bf16_f32 v41, v46, v47
	v_cvt_pk_bf16_f32 v42, v42, v43
	v_cvt_pk_bf16_f32 v43, v48, v49
	global_store_dwordx4 v[104:105], v[40:43], off offset:256
	s_waitcnt vmcnt(3)
	v_pk_mul_f32 v[48:49], v[114:115], v[114:115] op_sel:[0,1] op_sel_hi:[1,0]
	v_lshlrev_b32_e32 v44, 16, v110
	v_lshlrev_b32_e32 v40, 16, v108
	v_and_b32_e32 v41, 0xffff0000, v108
	v_lshlrev_b32_e32 v42, 16, v109
	v_and_b32_e32 v43, 0xffff0000, v109
	v_pk_fma_f32 v[42:43], v[114:115], v[42:43], v[48:49] op_sel:[1,0,0] op_sel_hi:[1,1,0] neg_lo:[0,0,1] neg_hi:[0,0,1]
	v_pk_fma_f32 v[40:41], v[114:115], v[40:41], v[48:49] op_sel:[1,0,0] op_sel_hi:[1,1,0] neg_lo:[0,0,1] neg_hi:[0,0,1]
	v_and_b32_e32 v45, 0xffff0000, v110
	v_lshlrev_b32_e32 v46, 16, v111
	v_and_b32_e32 v47, 0xffff0000, v111
	v_pk_fma_f32 v[40:41], v[90:91], v[40:41], v[94:95]
	v_pk_fma_f32 v[42:43], v[86:87], v[42:43], v[92:93]
	v_pk_fma_f32 v[36:37], v[36:37], v[76:77], v[40:41]
	v_pk_fma_f32 v[38:39], v[38:39], v[74:75], v[42:43]
	v_pk_fma_f32 v[40:41], v[114:115], v[46:47], v[48:49] op_sel:[1,0,0] op_sel_hi:[1,1,0] neg_lo:[0,0,1] neg_hi:[0,0,1]
	v_pk_fma_f32 v[42:43], v[114:115], v[44:45], v[48:49] op_sel:[1,0,0] op_sel_hi:[1,1,0] neg_lo:[0,0,1] neg_hi:[0,0,1]
	v_pk_fma_f32 v[40:41], v[70:71], v[40:41], v[82:83]
	v_pk_fma_f32 v[42:43], v[78:79], v[42:43], v[84:85]
	v_pk_fma_f32 v[40:41], v[34:35], v[66:67], v[40:41]
	v_pk_fma_f32 v[34:35], v[32:33], v[68:69], v[42:43]
	v_cvt_pk_bf16_f32 v32, v36, v37
	v_cvt_pk_bf16_f32 v33, v38, v39
	v_cvt_pk_bf16_f32 v34, v34, v35
	v_cvt_pk_bf16_f32 v35, v40, v41
	global_store_dwordx4 v[96:97], v[32:35], off offset:256
	global_load_dwordx4 v[32:35], v[98:99], off offset:256
	global_load_dwordx2 v[48:49], v[140:141], off offset:1024
	global_load_dwordx4 v[36:39], v[100:101], off offset:256
	global_load_dwordx2 v[50:51], v[140:141], off offset:1152
	global_load_dwordx4 v[40:43], v[102:103], off offset:256
	global_load_dwordx2 v[52:53], v[140:141], off offset:1280
	global_load_dwordx4 v[44:47], v[106:107], off offset:256
	global_load_dwordx2 v[54:55], v[140:141], off offset:1408
	s_waitcnt vmcnt(7)
	v_lshlrev_b32_e32 v56, 16, v32
	v_and_b32_e32 v57, 0xffff0000, v32
	v_lshlrev_b32_e32 v32, 16, v33
	v_and_b32_e32 v33, 0xffff0000, v33
	s_waitcnt vmcnt(6)
; #define PG8_BAR __builtin_amdgcn_s_barrier()
; __device__ __forceinline__ u32x4 pack8f(f32x4 lo, f32x4 hi) { u32x4 w; w.x = cvtpk(lo[0], lo[1]); w.y = cvtpk(lo[2], lo[3]); w.z = cvtpk(hi[0], hi[1]); w.w = cvtpk(hi[2], hi[3]); return w; }
;     ...
;         if (!has_next) break;
; #pragma unroll
;         for (int a = 0; a < 2; ++a)
; #pragma unroll
;             for (int b = 0; b < 2; ++b)
; #pragma unroll
;                 for (int m = 0; m < 4; ++m)
; #pragma unroll
;                     for (int n = 0; n < 2; ++n) acc[a][b][m][n] = (f32x4){0.f, 0.f, 0.f, 0.f};
;         cur = nxt; cA = nA; cB = nB; ++ui;
;         if constexpr (ALIGN) { if (wr == 1) PG8_BAR; }
;     }
;     __device__ __forceinline__ void operator()(const Acc& acc, const Unit& u, int wr, int wc, int fr, int fq) const {
;     ...
;                 for (int m = 0; m < 4; ++m) { const int row = rowb + hf * 128 + m * 16; yv[m] = *(const u32x4*)(y1 + yb + (size_t)(hf * 128 + m * 16) * 256 + bj * 128); st[m] = *(const f32x2*)(stats + (size_t)row * 2); }
; #pragma unroll
;                 for (int m = 0; m < 4; ++m) { const int row = rowb + hf * 128 + m * 16;
;                     f32x4 lo, hi; unpack8(yv[m], lo, hi); const float r = st[m][1], mr = st[m][0] * r;
;                     lo = (lo * r - mr) * G[0] + Bc[0] + gm[0] * acc[hf][bj][m][0]; hi = (hi * r - mr) * G[1] + Bc[1] + gm[1] * acc[hf][bj][m][1];
;                     *(u32x4*)(y2 + yb + (size_t)(hf * 128 + m * 16) * 256 + bj * 128) = pack8f(lo, hi); }
;                 asm volatile("" ::: "memory");
;             }
;             asm volatile("" ::: "memory");
;         }
	v_pk_mul_f32 v[60:61], v[48:49], v[48:49] op_sel:[0,1] op_sel_hi:[1,0]
	v_lshlrev_b32_e32 v58, 16, v34
	v_pk_fma_f32 v[32:33], v[48:49], v[32:33], v[60:61] op_sel:[1,0,0] op_sel_hi:[1,1,0] neg_lo:[0,0,1] neg_hi:[0,0,1]
	v_and_b32_e32 v59, 0xffff0000, v34
	v_lshlrev_b32_e32 v34, 16, v35
	v_and_b32_e32 v35, 0xffff0000, v35
	v_pk_fma_f32 v[32:33], v[86:87], v[32:33], v[92:93]
	v_pk_fma_f32 v[56:57], v[48:49], v[56:57], v[60:61] op_sel:[1,0,0] op_sel_hi:[1,1,0] neg_lo:[0,0,1] neg_hi:[0,0,1]
	v_pk_fma_f32 v[30:31], v[30:31], v[74:75], v[32:33]
	v_pk_fma_f32 v[32:33], v[48:49], v[34:35], v[60:61] op_sel:[1,0,0] op_sel_hi:[1,1,0] neg_lo:[0,0,1] neg_hi:[0,0,1]
	v_pk_fma_f32 v[34:35], v[48:49], v[58:59], v[60:61] op_sel:[1,0,0] op_sel_hi:[1,1,0] neg_lo:[0,0,1] neg_hi:[0,0,1]
	v_pk_fma_f32 v[56:57], v[90:91], v[56:57], v[94:95]
	v_pk_fma_f32 v[34:35], v[78:79], v[34:35], v[84:85]
	v_pk_fma_f32 v[32:33], v[70:71], v[32:33], v[82:83]
	v_pk_fma_f32 v[28:29], v[28:29], v[76:77], v[56:57]
	v_pk_fma_f32 v[32:33], v[26:27], v[66:67], v[32:33]
	v_pk_fma_f32 v[26:27], v[24:25], v[68:69], v[34:35]
	v_cvt_pk_bf16_f32 v24, v28, v29
	v_cvt_pk_bf16_f32 v25, v30, v31
	v_cvt_pk_bf16_f32 v26, v26, v27
	v_cvt_pk_bf16_f32 v27, v32, v33
	global_store_dwordx4 v[88:89], v[24:27], off offset:256
	s_waitcnt vmcnt(5)
	v_pk_mul_f32 v[32:33], v[50:51], v[50:51] op_sel:[0,1] op_sel_hi:[1,0]
	v_lshlrev_b32_e32 v28, 16, v38
	v_lshlrev_b32_e32 v24, 16, v36
	v_and_b32_e32 v25, 0xffff0000, v36
	v_lshlrev_b32_e32 v26, 16, v37
	v_and_b32_e32 v27, 0xffff0000, v37
	v_pk_fma_f32 v[26:27], v[50:51], v[26:27], v[32:33] op_sel:[1,0,0] op_sel_hi:[1,1,0] neg_lo:[0,0,1] neg_hi:[0,0,1]
	v_pk_fma_f32 v[24:25], v[50:51], v[24:25], v[32:33] op_sel:[1,0,0] op_sel_hi:[1,1,0] neg_lo:[0,0,1] neg_hi:[0,0,1]
	v_and_b32_e32 v29, 0xffff0000, v38
	v_lshlrev_b32_e32 v30, 16, v39
	v_and_b32_e32 v31, 0xffff0000, v39
	v_pk_fma_f32 v[24:25], v[90:91], v[24:25], v[94:95]
	v_pk_fma_f32 v[26:27], v[86:87], v[26:27], v[92:93]
	v_pk_fma_f32 v[20:21], v[20:21], v[76:77], v[24:25]
	v_pk_fma_f32 v[22:23], v[22:23], v[74:75], v[26:27]
	v_pk_fma_f32 v[24:25], v[50:51], v[30:31], v[32:33] op_sel:[1,0,0] op_sel_hi:[1,1,0] neg_lo:[0,0,1] neg_hi:[0,0,1]
	v_pk_fma_f32 v[26:27], v[50:51], v[28:29], v[32:33] op_sel:[1,0,0] op_sel_hi:[1,1,0] neg_lo:[0,0,1] neg_hi:[0,0,1]
	v_pk_fma_f32 v[24:25], v[70:71], v[24:25], v[82:83]
	v_pk_fma_f32 v[26:27], v[78:79], v[26:27], v[84:85]
	v_pk_fma_f32 v[24:25], v[18:19], v[66:67], v[24:25]
	v_pk_fma_f32 v[18:19], v[16:17], v[68:69], v[26:27]
	v_cvt_pk_bf16_f32 v16, v20, v21
	v_cvt_pk_bf16_f32 v17, v22, v23
	v_cvt_pk_bf16_f32 v18, v18, v19
	v_cvt_pk_bf16_f32 v19, v24, v25
	global_store_dwordx4 v[80:81], v[16:19], off offset:256
	s_waitcnt vmcnt(4)
	v_pk_mul_f32 v[24:25], v[52:53], v[52:53] op_sel:[0,1] op_sel_hi:[1,0]
	v_lshlrev_b32_e32 v20, 16, v42
	v_lshlrev_b32_e32 v16, 16, v40
	v_and_b32_e32 v17, 0xffff0000, v40
	v_lshlrev_b32_e32 v18, 16, v41
	v_and_b32_e32 v19, 0xffff0000, v41
	v_pk_fma_f32 v[18:19], v[52:53], v[18:19], v[24:25] op_sel:[1,0,0] op_sel_hi:[1,1,0] neg_lo:[0,0,1] neg_hi:[0,0,1]
	v_pk_fma_f32 v[16:17], v[52:53], v[16:17], v[24:25] op_sel:[1,0,0] op_sel_hi:[1,1,0] neg_lo:[0,0,1] neg_hi:[0,0,1]
	v_and_b32_e32 v21, 0xffff0000, v42
	v_lshlrev_b32_e32 v22, 16, v43
	v_and_b32_e32 v23, 0xffff0000, v43
	v_pk_fma_f32 v[16:17], v[90:91], v[16:17], v[94:95]
	v_pk_fma_f32 v[18:19], v[86:87], v[18:19], v[92:93]
	v_pk_fma_f32 v[12:13], v[12:13], v[76:77], v[16:17]
	v_pk_fma_f32 v[14:15], v[14:15], v[74:75], v[18:19]
	v_pk_fma_f32 v[16:17], v[52:53], v[22:23], v[24:25] op_sel:[1,0,0] op_sel_hi:[1,1,0] neg_lo:[0,0,1] neg_hi:[0,0,1]
	v_pk_fma_f32 v[18:19], v[52:53], v[20:21], v[24:25] op_sel:[1,0,0] op_sel_hi:[1,1,0] neg_lo:[0,0,1] neg_hi:[0,0,1]
	v_pk_fma_f32 v[16:17], v[70:71], v[16:17], v[82:83]
	v_pk_fma_f32 v[18:19], v[78:79], v[18:19], v[84:85]
	v_pk_fma_f32 v[16:17], v[10:11], v[66:67], v[16:17]
	v_pk_fma_f32 v[10:11], v[8:9], v[68:69], v[18:19]
	v_cvt_pk_bf16_f32 v8, v12, v13
	v_cvt_pk_bf16_f32 v9, v14, v15
	v_cvt_pk_bf16_f32 v10, v10, v11
	v_cvt_pk_bf16_f32 v11, v16, v17
	global_store_dwordx4 v[72:73], v[8:11], off offset:256
	s_waitcnt vmcnt(3)
	v_pk_mul_f32 v[16:17], v[54:55], v[54:55] op_sel:[0,1] op_sel_hi:[1,0]
	v_lshlrev_b32_e32 v12, 16, v46
	v_lshlrev_b32_e32 v8, 16, v44
	v_and_b32_e32 v9, 0xffff0000, v44
	v_lshlrev_b32_e32 v10, 16, v45
	v_and_b32_e32 v11, 0xffff0000, v45
	v_pk_fma_f32 v[10:11], v[54:55], v[10:11], v[16:17] op_sel:[1,0,0] op_sel_hi:[1,1,0] neg_lo:[0,0,1] neg_hi:[0,0,1]
	v_pk_fma_f32 v[8:9], v[54:55], v[8:9], v[16:17] op_sel:[1,0,0] op_sel_hi:[1,1,0] neg_lo:[0,0,1] neg_hi:[0,0,1]
	v_and_b32_e32 v13, 0xffff0000, v46
	v_lshlrev_b32_e32 v14, 16, v47
	v_and_b32_e32 v15, 0xffff0000, v47
	v_pk_fma_f32 v[8:9], v[90:91], v[8:9], v[94:95]
	v_pk_fma_f32 v[10:11], v[86:87], v[10:11], v[92:93]
	v_pk_fma_f32 v[4:5], v[4:5], v[76:77], v[8:9]
	v_pk_fma_f32 v[6:7], v[6:7], v[74:75], v[10:11]
	v_pk_fma_f32 v[8:9], v[54:55], v[14:15], v[16:17] op_sel:[1,0,0] op_sel_hi:[1,1,0] neg_lo:[0,0,1] neg_hi:[0,0,1]
	v_pk_fma_f32 v[10:11], v[54:55], v[12:13], v[16:17] op_sel:[1,0,0] op_sel_hi:[1,1,0] neg_lo:[0,0,1] neg_hi:[0,0,1]
	v_pk_fma_f32 v[8:9], v[70:71], v[8:9], v[82:83]
	v_pk_fma_f32 v[10:11], v[78:79], v[10:11], v[84:85]
	v_pk_fma_f32 v[8:9], v[2:3], v[66:67], v[8:9]
	v_pk_fma_f32 v[2:3], v[0:1], v[68:69], v[10:11]
	v_cvt_pk_bf16_f32 v0, v4, v5
	v_cvt_pk_bf16_f32 v1, v6, v7
	v_cvt_pk_bf16_f32 v2, v2, v3
	v_cvt_pk_bf16_f32 v3, v8, v9
	global_store_dwordx4 v[64:65], v[0:3], off offset:256
	s_cbranch_vccz .LBB0_1274
	s_waitcnt vmcnt(0)
	s_cmpk_gt_u32 s29, 0xff
	s_cbranch_scc1 .LBB0_1285
	s_barrier
